# adds 32-bit offset store addressing in the SwiGLU (gate/up) GEMM epilogue on top of the previous version
# baseline (speedup 1.0000x reference)
.LBB0_1832:
	v_lshl_add_u32 v144, s10, 8, v148
	v_ashrrev_i32_e32 v145, 31, v144
	v_lshl_add_u64 v[146:147], v[144:145], 3, s[12:13]
	global_load_dwordx2 v[156:157], v[146:147], off
	v_mov_b32_e32 v160, v124
	v_mov_b32_e32 v124, v126
	v_mov_b32_e32 v126, v120
	v_mov_b32_e32 v162, v122
	v_mov_b32_e32 v161, v116
	v_mov_b32_e32 v116, v125
	v_mov_b32_e32 v125, v118
	v_mov_b32_e32 v118, v127
	v_mov_b32_e32 v127, v112
	v_mov_b32_e32 v112, v121
	v_mov_b32_e32 v163, v114
	v_mov_b32_e32 v114, v123
	v_lshl_or_b32 v158, s11, 7, v150
	v_ashrrev_i32_e32 v159, 31, v158
	s_waitcnt vmcnt(0)
	v_ffbh_u32_e32 v120, v157
	v_min_u32_e32 v122, 32, v120
	v_lshlrev_b64 v[120:121], v122, v[156:157]
	v_min_u32_e32 v120, 1, v120
	v_or_b32_e32 v120, v121, v120
	v_cvt_f32_u32_e32 v123, v120
	v_sub_u32_e32 v122, 32, v122
	s_nop 0
	s_nop 0
	s_nop 0
	v_ldexp_f32 v122, v123, v122
	v_fmamk_f32 v122, v122, 0x30800000, v154
	v_mul_f32_e32 v123, 0x4b800000, v122
	v_cmp_gt_f32_e32 vcc, s56, v122
	s_nop 1
	v_cndmask_b32_e32 v122, v122, v123, vcc
	v_rsq_f32_e32 v145, v122
	v_lshlrev_b32_e64 v122, 1, v158
	v_mad_u32_u24 v156, v144, s57, v122
	v_mul_f32_e32 v155, 0x45800000, v145
	v_cndmask_b32_e32 v158, v145, v155, vcc
	v_pk_mul_f32 v[114:115], v[114:115], v[158:159] op_sel_hi:[1,0]
	v_pk_mul_f32 v[160:161], v[160:161], v[158:159] op_sel_hi:[1,0]
	v_pk_mul_f32 v[116:117], v[116:117], v[158:159] op_sel_hi:[1,0]
	v_pk_mul_f32 v[124:125], v[124:125], v[158:159] op_sel_hi:[1,0]
	v_pk_mul_f32 v[118:119], v[118:119], v[158:159] op_sel_hi:[1,0]
	v_pk_mul_f32 v[126:127], v[126:127], v[158:159] op_sel_hi:[1,0]
	v_pk_mul_f32 v[112:113], v[112:113], v[158:159] op_sel_hi:[1,0]
	v_pk_mul_f32 v[162:163], v[162:163], v[158:159] op_sel_hi:[1,0]
	v_mul_f32_e32 v167, 0xbfb8aa3b, v115
	v_mul_f32_e32 v145, 0xbfb8aa3b, v161
	v_mul_f32_e32 v155, 0xbfb8aa3b, v117
	v_mul_f32_e32 v158, 0xbfb8aa3b, v125
	v_mul_f32_e32 v159, 0xbfb8aa3b, v119
	v_mul_f32_e32 v164, 0xbfb8aa3b, v127
	v_mul_f32_e32 v165, 0xbfb8aa3b, v113
	v_mul_f32_e32 v166, 0xbfb8aa3b, v163
	v_exp_f32_e32 v167, v167
	v_exp_f32_e32 v145, v145
	v_exp_f32_e32 v155, v155
	v_exp_f32_e32 v158, v158
	v_exp_f32_e32 v159, v159
	v_exp_f32_e32 v164, v164
	v_exp_f32_e32 v165, v165
	v_exp_f32_e32 v166, v166
	v_add_f32_e32 v167, 1.0, v167
	v_add_f32_e32 v145, 1.0, v145
	v_add_f32_e32 v155, 1.0, v155
	v_add_f32_e32 v158, 1.0, v158
	v_add_f32_e32 v159, 1.0, v159
	v_add_f32_e32 v164, 1.0, v164
	v_add_f32_e32 v165, 1.0, v165
	v_add_f32_e32 v166, 1.0, v166
	v_rcp_f32_e32 v167, v167
	v_rcp_f32_e32 v145, v145
	v_rcp_f32_e32 v155, v155
	v_rcp_f32_e32 v158, v158
	v_rcp_f32_e32 v159, v159
	v_rcp_f32_e32 v164, v164
	v_rcp_f32_e32 v165, v165
	v_rcp_f32_e32 v166, v166
	v_mul_f32_e32 v115, v115, v167
	v_mul_f32_e32 v145, v161, v145
	v_mul_f32_e32 v117, v117, v155
	v_mul_f32_e32 v125, v125, v158
	v_mul_f32_e32 v119, v119, v159
	v_mul_f32_e32 v127, v127, v164
	v_mul_f32_e32 v113, v113, v165
	v_mul_f32_e32 v155, v163, v166
	v_mul_f32_e32 v115, v114, v115
	v_mul_f32_e32 v145, v160, v145
	v_mul_f32_e32 v116, v116, v117
	v_mul_f32_e32 v117, v124, v125
	v_mul_f32_e32 v118, v118, v119
	v_mul_f32_e32 v119, v126, v127
	v_mul_f32_e32 v124, v112, v113
	v_mul_f32_e32 v125, v162, v155
	v_cvt_pk_bf16_f32 v112, v145, v116
	v_cvt_pk_bf16_f32 v113, v117, v118
	v_cvt_pk_bf16_f32 v114, v119, v124
	v_cvt_pk_bf16_f32 v115, v125, v115
	global_store_dwordx4 v156, v[112:115], s[18:19]
	global_load_dwordx2 v[112:113], v[146:147], off offset:128
	s_nop 0
	v_mov_b32_e32 v115, v104
	v_mov_b32_e32 v104, v109
	v_mov_b32_e32 v109, v106
	v_mov_b32_e32 v106, v111
	v_mov_b32_e32 v111, v96
	v_mov_b32_e32 v96, v101
	v_mov_b32_e32 v101, v98
	v_mov_b32_e32 v114, v108
	v_mov_b32_e32 v108, v110
	v_mov_b32_e32 v110, v100
	v_mov_b32_e32 v100, v102
	s_waitcnt vmcnt(0)
	v_ffbh_u32_e32 v98, v113
	v_min_u32_e32 v102, 32, v98
	v_lshlrev_b64 v[112:113], v102, v[112:113]
	v_min_u32_e32 v98, 1, v112
	v_or_b32_e32 v98, v113, v98
	v_cvt_f32_u32_e32 v112, v98
	v_sub_u32_e32 v102, 32, v102
	v_mov_b32_e32 v98, v103
	v_or_b32_e32 v103, 16, v144
	v_ldexp_f32 v102, v112, v102
	v_fmamk_f32 v102, v102, 0x30800000, v154
	v_mul_f32_e32 v112, 0x4b800000, v102
	v_cmp_gt_f32_e32 vcc, s56, v102
	s_nop 1
	v_cndmask_b32_e32 v102, v102, v112, vcc
	v_rsq_f32_e32 v112, v102
	v_mad_u32_u24 v102, v103, s57, v122
	s_nop 0
	s_nop 0
	v_mul_f32_e32 v113, 0x45800000, v112
	v_cndmask_b32_e32 v112, v112, v113, vcc
	v_pk_mul_f32 v[98:99], v[98:99], v[112:113] op_sel_hi:[1,0]
	v_pk_mul_f32 v[114:115], v[114:115], v[112:113] op_sel_hi:[1,0]
	v_pk_mul_f32 v[104:105], v[104:105], v[112:113] op_sel_hi:[1,0]
	v_pk_mul_f32 v[108:109], v[108:109], v[112:113] op_sel_hi:[1,0]
	v_pk_mul_f32 v[106:107], v[106:107], v[112:113] op_sel_hi:[1,0]
	v_pk_mul_f32 v[110:111], v[110:111], v[112:113] op_sel_hi:[1,0]
	v_pk_mul_f32 v[96:97], v[96:97], v[112:113] op_sel_hi:[1,0]
	v_pk_mul_f32 v[100:101], v[100:101], v[112:113] op_sel_hi:[1,0]
	v_mul_f32_e32 v125, 0xbfb8aa3b, v99
	v_mul_f32_e32 v112, 0xbfb8aa3b, v115
	v_mul_f32_e32 v113, 0xbfb8aa3b, v105
	v_mul_f32_e32 v116, 0xbfb8aa3b, v109
	v_mul_f32_e32 v117, 0xbfb8aa3b, v107
	v_mul_f32_e32 v118, 0xbfb8aa3b, v111
	v_mul_f32_e32 v119, 0xbfb8aa3b, v97
	v_mul_f32_e32 v124, 0xbfb8aa3b, v101
	v_exp_f32_e32 v125, v125
	v_exp_f32_e32 v112, v112
	v_exp_f32_e32 v113, v113
	v_exp_f32_e32 v116, v116
	v_exp_f32_e32 v117, v117
	v_exp_f32_e32 v118, v118
	v_exp_f32_e32 v119, v119
	v_exp_f32_e32 v124, v124
	v_add_f32_e32 v125, 1.0, v125
	v_add_f32_e32 v112, 1.0, v112
	v_add_f32_e32 v113, 1.0, v113
	v_add_f32_e32 v116, 1.0, v116
	v_add_f32_e32 v117, 1.0, v117
	v_add_f32_e32 v118, 1.0, v118
	v_add_f32_e32 v119, 1.0, v119
	v_add_f32_e32 v124, 1.0, v124
	v_rcp_f32_e32 v125, v125
	v_rcp_f32_e32 v112, v112
	v_rcp_f32_e32 v113, v113
	v_rcp_f32_e32 v116, v116
	v_rcp_f32_e32 v117, v117
	v_rcp_f32_e32 v118, v118
	v_rcp_f32_e32 v119, v119
	v_rcp_f32_e32 v124, v124
	v_mul_f32_e32 v99, v99, v125
	v_mul_f32_e32 v112, v115, v112
	v_mul_f32_e32 v105, v105, v113
	v_mul_f32_e32 v109, v109, v116
	v_mul_f32_e32 v107, v107, v117
	v_mul_f32_e32 v111, v111, v118
	v_mul_f32_e32 v97, v97, v119
	v_mul_f32_e32 v101, v101, v124
	v_mul_f32_e32 v99, v98, v99
	v_mul_f32_e32 v112, v114, v112
	v_mul_f32_e32 v104, v104, v105
	v_mul_f32_e32 v105, v108, v109
	v_mul_f32_e32 v106, v106, v107
	v_mul_f32_e32 v107, v110, v111
	v_mul_f32_e32 v108, v96, v97
	v_mul_f32_e32 v100, v100, v101
	v_cvt_pk_bf16_f32 v96, v112, v104
	v_cvt_pk_bf16_f32 v97, v105, v106
	v_cvt_pk_bf16_f32 v98, v107, v108
	v_cvt_pk_bf16_f32 v99, v100, v99
	global_store_dwordx4 v102, v[96:99], s[18:19]
	global_load_dwordx2 v[96:97], v[146:147], off offset:256
	s_nop 0
	v_mov_b32_e32 v99, v88
	v_mov_b32_e32 v88, v93
	v_mov_b32_e32 v93, v90
	v_mov_b32_e32 v90, v95
	v_mov_b32_e32 v95, v80
	v_mov_b32_e32 v80, v85
	v_mov_b32_e32 v85, v82
	v_mov_b32_e32 v98, v92
	v_mov_b32_e32 v92, v94
	v_mov_b32_e32 v94, v84
	v_mov_b32_e32 v84, v86
	s_waitcnt vmcnt(0)
	v_ffbh_u32_e32 v82, v97
	v_min_u32_e32 v86, 32, v82
	v_lshlrev_b64 v[96:97], v86, v[96:97]
	v_min_u32_e32 v82, 1, v96
	v_or_b32_e32 v82, v97, v82
	v_cvt_f32_u32_e32 v96, v82
	v_sub_u32_e32 v86, 32, v86
	v_mov_b32_e32 v82, v87
	v_or_b32_e32 v87, 32, v144
	v_ldexp_f32 v86, v96, v86
	v_fmamk_f32 v86, v86, 0x30800000, v154
	v_mul_f32_e32 v96, 0x4b800000, v86
	v_cmp_gt_f32_e32 vcc, s56, v86
	s_nop 1
	v_cndmask_b32_e32 v86, v86, v96, vcc
	v_rsq_f32_e32 v96, v86
	v_mad_u32_u24 v86, v87, s57, v122
	s_nop 0
	s_nop 0
	v_mul_f32_e32 v97, 0x45800000, v96
	v_cndmask_b32_e32 v96, v96, v97, vcc
	v_pk_mul_f32 v[82:83], v[82:83], v[96:97] op_sel_hi:[1,0]
	v_pk_mul_f32 v[98:99], v[98:99], v[96:97] op_sel_hi:[1,0]
	v_pk_mul_f32 v[88:89], v[88:89], v[96:97] op_sel_hi:[1,0]
	v_pk_mul_f32 v[92:93], v[92:93], v[96:97] op_sel_hi:[1,0]
	v_pk_mul_f32 v[90:91], v[90:91], v[96:97] op_sel_hi:[1,0]
	v_pk_mul_f32 v[94:95], v[94:95], v[96:97] op_sel_hi:[1,0]
	v_pk_mul_f32 v[80:81], v[80:81], v[96:97] op_sel_hi:[1,0]
	v_pk_mul_f32 v[84:85], v[84:85], v[96:97] op_sel_hi:[1,0]
	v_mul_f32_e32 v105, 0xbfb8aa3b, v83
	v_mul_f32_e32 v96, 0xbfb8aa3b, v99
	v_mul_f32_e32 v97, 0xbfb8aa3b, v89
	v_mul_f32_e32 v100, 0xbfb8aa3b, v93
	v_mul_f32_e32 v101, 0xbfb8aa3b, v91
	v_mul_f32_e32 v102, 0xbfb8aa3b, v95
	v_mul_f32_e32 v103, 0xbfb8aa3b, v81
	v_mul_f32_e32 v104, 0xbfb8aa3b, v85
	v_exp_f32_e32 v105, v105
	v_exp_f32_e32 v96, v96
	v_exp_f32_e32 v97, v97
	v_exp_f32_e32 v100, v100
	v_exp_f32_e32 v101, v101
	v_exp_f32_e32 v102, v102
	v_exp_f32_e32 v103, v103
	v_exp_f32_e32 v104, v104
	v_add_f32_e32 v105, 1.0, v105
	v_add_f32_e32 v96, 1.0, v96
	v_add_f32_e32 v97, 1.0, v97
	v_add_f32_e32 v100, 1.0, v100
	v_add_f32_e32 v101, 1.0, v101
	v_add_f32_e32 v102, 1.0, v102
	v_add_f32_e32 v103, 1.0, v103
	v_add_f32_e32 v104, 1.0, v104
	v_rcp_f32_e32 v105, v105
	v_rcp_f32_e32 v96, v96
	v_rcp_f32_e32 v97, v97
	v_rcp_f32_e32 v100, v100
	v_rcp_f32_e32 v101, v101
	v_rcp_f32_e32 v102, v102
	v_rcp_f32_e32 v103, v103
	v_rcp_f32_e32 v104, v104
	v_mul_f32_e32 v83, v83, v105
	v_mul_f32_e32 v96, v99, v96
	v_mul_f32_e32 v89, v89, v97
	v_mul_f32_e32 v93, v93, v100
	v_mul_f32_e32 v91, v91, v101
	v_mul_f32_e32 v95, v95, v102
	v_mul_f32_e32 v81, v81, v103
	v_mul_f32_e32 v85, v85, v104
	v_mul_f32_e32 v83, v82, v83
	v_mul_f32_e32 v96, v98, v96
	v_mul_f32_e32 v88, v88, v89
	v_mul_f32_e32 v89, v92, v93
	v_mul_f32_e32 v90, v90, v91
	v_mul_f32_e32 v91, v94, v95
	v_mul_f32_e32 v92, v80, v81
	v_mul_f32_e32 v84, v84, v85
	v_cvt_pk_bf16_f32 v80, v96, v88
	v_cvt_pk_bf16_f32 v81, v89, v90
	v_cvt_pk_bf16_f32 v82, v91, v92
	v_cvt_pk_bf16_f32 v83, v84, v83
	global_store_dwordx4 v86, v[80:83], s[18:19]
	global_load_dwordx2 v[80:81], v[146:147], off offset:384
	s_nop 0
	v_mov_b32_e32 v83, v72
	v_mov_b32_e32 v72, v77
	v_mov_b32_e32 v77, v74
	v_mov_b32_e32 v74, v79
	v_mov_b32_e32 v79, v64
	v_mov_b32_e32 v64, v69
	v_mov_b32_e32 v69, v66
	v_mov_b32_e32 v82, v76
	v_mov_b32_e32 v76, v78
	v_mov_b32_e32 v78, v68
	v_mov_b32_e32 v68, v70
	s_waitcnt vmcnt(0)
	v_ffbh_u32_e32 v66, v81
	v_min_u32_e32 v70, 32, v66
	v_lshlrev_b64 v[80:81], v70, v[80:81]
	v_min_u32_e32 v66, 1, v80
	v_or_b32_e32 v66, v81, v66
	v_cvt_f32_u32_e32 v80, v66
	v_sub_u32_e32 v70, 32, v70
	v_mov_b32_e32 v66, v71
	v_or_b32_e32 v71, 48, v144
	v_ldexp_f32 v70, v80, v70
	v_fmamk_f32 v70, v70, 0x30800000, v154
	v_mul_f32_e32 v80, 0x4b800000, v70
	v_cmp_gt_f32_e32 vcc, s56, v70
	s_nop 1
	v_cndmask_b32_e32 v70, v70, v80, vcc
	v_rsq_f32_e32 v80, v70
	v_mad_u32_u24 v70, v71, s57, v122
	s_nop 0
	s_nop 0
	v_mul_f32_e32 v81, 0x45800000, v80
	v_cndmask_b32_e32 v80, v80, v81, vcc
	v_pk_mul_f32 v[66:67], v[66:67], v[80:81] op_sel_hi:[1,0]
	v_pk_mul_f32 v[82:83], v[82:83], v[80:81] op_sel_hi:[1,0]
	v_pk_mul_f32 v[72:73], v[72:73], v[80:81] op_sel_hi:[1,0]
	v_pk_mul_f32 v[76:77], v[76:77], v[80:81] op_sel_hi:[1,0]
	v_pk_mul_f32 v[74:75], v[74:75], v[80:81] op_sel_hi:[1,0]
	v_pk_mul_f32 v[78:79], v[78:79], v[80:81] op_sel_hi:[1,0]
	v_pk_mul_f32 v[64:65], v[64:65], v[80:81] op_sel_hi:[1,0]
	v_pk_mul_f32 v[68:69], v[68:69], v[80:81] op_sel_hi:[1,0]
	v_mul_f32_e32 v89, 0xbfb8aa3b, v67
	v_mul_f32_e32 v80, 0xbfb8aa3b, v83
	v_mul_f32_e32 v81, 0xbfb8aa3b, v73
	v_mul_f32_e32 v84, 0xbfb8aa3b, v77
	v_mul_f32_e32 v85, 0xbfb8aa3b, v75
	v_mul_f32_e32 v86, 0xbfb8aa3b, v79
	v_mul_f32_e32 v87, 0xbfb8aa3b, v65
	v_mul_f32_e32 v88, 0xbfb8aa3b, v69
	v_exp_f32_e32 v89, v89
	v_exp_f32_e32 v80, v80
	v_exp_f32_e32 v81, v81
	v_exp_f32_e32 v84, v84
	v_exp_f32_e32 v85, v85
	v_exp_f32_e32 v86, v86
	v_exp_f32_e32 v87, v87
	v_exp_f32_e32 v88, v88
	v_add_f32_e32 v89, 1.0, v89
	v_add_f32_e32 v80, 1.0, v80
	v_add_f32_e32 v81, 1.0, v81
	v_add_f32_e32 v84, 1.0, v84
	v_add_f32_e32 v85, 1.0, v85
	v_add_f32_e32 v86, 1.0, v86
	v_add_f32_e32 v87, 1.0, v87
	v_add_f32_e32 v88, 1.0, v88
	v_rcp_f32_e32 v89, v89
	v_rcp_f32_e32 v80, v80
	v_rcp_f32_e32 v81, v81
	v_rcp_f32_e32 v84, v84
	v_rcp_f32_e32 v85, v85
	v_rcp_f32_e32 v86, v86
	v_rcp_f32_e32 v87, v87
	v_rcp_f32_e32 v88, v88
	v_mul_f32_e32 v67, v67, v89
	v_mul_f32_e32 v80, v83, v80
	v_mul_f32_e32 v73, v73, v81
	v_mul_f32_e32 v77, v77, v84
	v_mul_f32_e32 v75, v75, v85
	v_mul_f32_e32 v79, v79, v86
	v_mul_f32_e32 v65, v65, v87
	v_mul_f32_e32 v69, v69, v88
	v_mul_f32_e32 v67, v66, v67
	v_mul_f32_e32 v80, v82, v80
	v_mul_f32_e32 v72, v72, v73
	v_mul_f32_e32 v73, v76, v77
	v_mul_f32_e32 v74, v74, v75
	v_mul_f32_e32 v75, v78, v79
	v_mul_f32_e32 v76, v64, v65
	v_mul_f32_e32 v68, v68, v69
	v_cvt_pk_bf16_f32 v64, v80, v72
	v_cvt_pk_bf16_f32 v65, v73, v74
	v_cvt_pk_bf16_f32 v66, v75, v76
	v_cvt_pk_bf16_f32 v67, v68, v67
	global_store_dwordx4 v70, v[64:67], s[18:19]
	global_load_dwordx2 v[64:65], v[146:147], off offset:1024
	s_nop 0
	v_mov_b32_e32 v67, v56
	v_mov_b32_e32 v56, v61
	v_mov_b32_e32 v61, v58
	v_mov_b32_e32 v58, v63
	v_mov_b32_e32 v63, v48
	v_mov_b32_e32 v48, v53
	v_mov_b32_e32 v53, v50
	v_mov_b32_e32 v66, v60
	v_mov_b32_e32 v60, v62
	v_mov_b32_e32 v62, v52
	v_mov_b32_e32 v52, v54
	s_waitcnt vmcnt(0)
	v_ffbh_u32_e32 v50, v65
	v_min_u32_e32 v54, 32, v50
	v_lshlrev_b64 v[64:65], v54, v[64:65]
	v_min_u32_e32 v50, 1, v64
	v_or_b32_e32 v50, v65, v50
	v_cvt_f32_u32_e32 v64, v50
	v_sub_u32_e32 v54, 32, v54
	v_mov_b32_e32 v50, v55
	v_add_u32_e32 v55, 0x80, v144
	v_ldexp_f32 v54, v64, v54
	v_fmamk_f32 v54, v54, 0x30800000, v154
	v_mul_f32_e32 v64, 0x4b800000, v54
	v_cmp_gt_f32_e32 vcc, s56, v54
	s_nop 1
	v_cndmask_b32_e32 v54, v54, v64, vcc
	v_rsq_f32_e32 v64, v54
	v_mad_u32_u24 v54, v55, s57, v122
	s_nop 0
	s_nop 0
	v_mul_f32_e32 v65, 0x45800000, v64
	v_cndmask_b32_e32 v64, v64, v65, vcc
	v_pk_mul_f32 v[50:51], v[50:51], v[64:65] op_sel_hi:[1,0]
	v_pk_mul_f32 v[66:67], v[66:67], v[64:65] op_sel_hi:[1,0]
	v_pk_mul_f32 v[56:57], v[56:57], v[64:65] op_sel_hi:[1,0]
	v_pk_mul_f32 v[60:61], v[60:61], v[64:65] op_sel_hi:[1,0]
	v_pk_mul_f32 v[58:59], v[58:59], v[64:65] op_sel_hi:[1,0]
	v_pk_mul_f32 v[62:63], v[62:63], v[64:65] op_sel_hi:[1,0]
	v_pk_mul_f32 v[48:49], v[48:49], v[64:65] op_sel_hi:[1,0]
	v_pk_mul_f32 v[52:53], v[52:53], v[64:65] op_sel_hi:[1,0]
	v_mul_f32_e32 v73, 0xbfb8aa3b, v51
	v_mul_f32_e32 v64, 0xbfb8aa3b, v67
	v_mul_f32_e32 v65, 0xbfb8aa3b, v57
	v_mul_f32_e32 v68, 0xbfb8aa3b, v61
	v_mul_f32_e32 v69, 0xbfb8aa3b, v59
	v_mul_f32_e32 v70, 0xbfb8aa3b, v63
	v_mul_f32_e32 v71, 0xbfb8aa3b, v49
	v_mul_f32_e32 v72, 0xbfb8aa3b, v53
	v_exp_f32_e32 v73, v73
	v_exp_f32_e32 v64, v64
	v_exp_f32_e32 v65, v65
	v_exp_f32_e32 v68, v68
	v_exp_f32_e32 v69, v69
	v_exp_f32_e32 v70, v70
	v_exp_f32_e32 v71, v71
	v_exp_f32_e32 v72, v72
	v_add_f32_e32 v73, 1.0, v73
	v_add_f32_e32 v64, 1.0, v64
	v_add_f32_e32 v65, 1.0, v65
	v_add_f32_e32 v68, 1.0, v68
	v_add_f32_e32 v69, 1.0, v69
	v_add_f32_e32 v70, 1.0, v70
	v_add_f32_e32 v71, 1.0, v71
	v_add_f32_e32 v72, 1.0, v72
	v_rcp_f32_e32 v73, v73
	v_rcp_f32_e32 v64, v64
	v_rcp_f32_e32 v65, v65
	v_rcp_f32_e32 v68, v68
	v_rcp_f32_e32 v69, v69
	v_rcp_f32_e32 v70, v70
	v_rcp_f32_e32 v71, v71
	v_rcp_f32_e32 v72, v72
	v_mul_f32_e32 v51, v51, v73
	v_mul_f32_e32 v64, v67, v64
	v_mul_f32_e32 v57, v57, v65
	v_mul_f32_e32 v61, v61, v68
	v_mul_f32_e32 v59, v59, v69
	v_mul_f32_e32 v63, v63, v70
	v_mul_f32_e32 v49, v49, v71
	v_mul_f32_e32 v53, v53, v72
	v_mul_f32_e32 v51, v50, v51
	v_mul_f32_e32 v64, v66, v64
	v_mul_f32_e32 v56, v56, v57
	v_mul_f32_e32 v57, v60, v61
	v_mul_f32_e32 v58, v58, v59
	v_mul_f32_e32 v59, v62, v63
	v_mul_f32_e32 v60, v48, v49
	v_mul_f32_e32 v52, v52, v53
	v_cvt_pk_bf16_f32 v48, v64, v56
	v_cvt_pk_bf16_f32 v49, v57, v58
	v_cvt_pk_bf16_f32 v50, v59, v60
	v_cvt_pk_bf16_f32 v51, v52, v51
	global_store_dwordx4 v54, v[48:51], s[18:19]
	global_load_dwordx2 v[48:49], v[146:147], off offset:1152
	s_nop 0
	v_mov_b32_e32 v51, v40
	v_mov_b32_e32 v40, v45
	v_mov_b32_e32 v45, v42
	v_mov_b32_e32 v42, v47
	v_mov_b32_e32 v47, v32
	v_mov_b32_e32 v32, v37
	v_mov_b32_e32 v37, v34
	v_mov_b32_e32 v50, v44
	v_mov_b32_e32 v44, v46
	v_mov_b32_e32 v46, v36
	v_mov_b32_e32 v36, v38
	s_waitcnt vmcnt(0)
	v_ffbh_u32_e32 v34, v49
	v_min_u32_e32 v38, 32, v34
	v_lshlrev_b64 v[48:49], v38, v[48:49]
	v_min_u32_e32 v34, 1, v48
	v_or_b32_e32 v34, v49, v34
	v_cvt_f32_u32_e32 v48, v34
	v_sub_u32_e32 v38, 32, v38
	v_mov_b32_e32 v34, v39
	v_add_u32_e32 v39, 0x90, v144
	v_ldexp_f32 v38, v48, v38
	v_fmamk_f32 v38, v38, 0x30800000, v154
	v_mul_f32_e32 v48, 0x4b800000, v38
	v_cmp_gt_f32_e32 vcc, s56, v38
	s_nop 1
	v_cndmask_b32_e32 v38, v38, v48, vcc
	v_rsq_f32_e32 v48, v38
	v_mad_u32_u24 v38, v39, s57, v122
	s_nop 0
	s_nop 0
	v_mul_f32_e32 v49, 0x45800000, v48
	v_cndmask_b32_e32 v48, v48, v49, vcc
	v_pk_mul_f32 v[34:35], v[34:35], v[48:49] op_sel_hi:[1,0]
	v_pk_mul_f32 v[50:51], v[50:51], v[48:49] op_sel_hi:[1,0]
	v_pk_mul_f32 v[40:41], v[40:41], v[48:49] op_sel_hi:[1,0]
	v_pk_mul_f32 v[44:45], v[44:45], v[48:49] op_sel_hi:[1,0]
	v_pk_mul_f32 v[42:43], v[42:43], v[48:49] op_sel_hi:[1,0]
	v_pk_mul_f32 v[46:47], v[46:47], v[48:49] op_sel_hi:[1,0]
	v_pk_mul_f32 v[32:33], v[32:33], v[48:49] op_sel_hi:[1,0]
	v_pk_mul_f32 v[36:37], v[36:37], v[48:49] op_sel_hi:[1,0]
	v_mul_f32_e32 v57, 0xbfb8aa3b, v35
	v_mul_f32_e32 v48, 0xbfb8aa3b, v51
	v_mul_f32_e32 v49, 0xbfb8aa3b, v41
	v_mul_f32_e32 v52, 0xbfb8aa3b, v45
	v_mul_f32_e32 v53, 0xbfb8aa3b, v43
	v_mul_f32_e32 v54, 0xbfb8aa3b, v47
	v_mul_f32_e32 v55, 0xbfb8aa3b, v33
	v_mul_f32_e32 v56, 0xbfb8aa3b, v37
	v_exp_f32_e32 v57, v57
	v_exp_f32_e32 v48, v48
	v_exp_f32_e32 v49, v49
	v_exp_f32_e32 v52, v52
	v_exp_f32_e32 v53, v53
	v_exp_f32_e32 v54, v54
	v_exp_f32_e32 v55, v55
	v_exp_f32_e32 v56, v56
	v_add_f32_e32 v57, 1.0, v57
	v_add_f32_e32 v48, 1.0, v48
	v_add_f32_e32 v49, 1.0, v49
	v_add_f32_e32 v52, 1.0, v52
	v_add_f32_e32 v53, 1.0, v53
	v_add_f32_e32 v54, 1.0, v54
	v_add_f32_e32 v55, 1.0, v55
	v_add_f32_e32 v56, 1.0, v56
	v_rcp_f32_e32 v57, v57
	v_rcp_f32_e32 v48, v48
	v_rcp_f32_e32 v49, v49
	v_rcp_f32_e32 v52, v52
	v_rcp_f32_e32 v53, v53
	v_rcp_f32_e32 v54, v54
	v_rcp_f32_e32 v55, v55
	v_rcp_f32_e32 v56, v56
	v_mul_f32_e32 v35, v35, v57
	v_mul_f32_e32 v48, v51, v48
	v_mul_f32_e32 v41, v41, v49
	v_mul_f32_e32 v45, v45, v52
	v_mul_f32_e32 v43, v43, v53
	v_mul_f32_e32 v47, v47, v54
	v_mul_f32_e32 v33, v33, v55
	v_mul_f32_e32 v37, v37, v56
	v_mul_f32_e32 v35, v34, v35
	v_mul_f32_e32 v48, v50, v48
	v_mul_f32_e32 v40, v40, v41
	v_mul_f32_e32 v41, v44, v45
	v_mul_f32_e32 v42, v42, v43
	v_mul_f32_e32 v43, v46, v47
	v_mul_f32_e32 v44, v32, v33
	v_mul_f32_e32 v36, v36, v37
	v_cvt_pk_bf16_f32 v32, v48, v40
	v_cvt_pk_bf16_f32 v33, v41, v42
	v_cvt_pk_bf16_f32 v34, v43, v44
	v_cvt_pk_bf16_f32 v35, v36, v35
	global_store_dwordx4 v38, v[32:35], s[18:19]
	global_load_dwordx2 v[32:33], v[146:147], off offset:1280
	s_nop 0
	v_mov_b32_e32 v35, v24
	v_mov_b32_e32 v24, v29
	v_mov_b32_e32 v29, v26
	v_mov_b32_e32 v26, v31
	v_mov_b32_e32 v31, v16
	v_mov_b32_e32 v16, v21
	v_mov_b32_e32 v21, v18
	v_mov_b32_e32 v34, v28
	v_mov_b32_e32 v28, v30
	v_mov_b32_e32 v30, v20
	v_mov_b32_e32 v20, v22
	s_waitcnt vmcnt(0)
	v_ffbh_u32_e32 v18, v33
	v_min_u32_e32 v22, 32, v18
	v_lshlrev_b64 v[32:33], v22, v[32:33]
	v_min_u32_e32 v18, 1, v32
	v_or_b32_e32 v18, v33, v18
	v_cvt_f32_u32_e32 v32, v18
	v_sub_u32_e32 v22, 32, v22
	v_mov_b32_e32 v18, v23
	v_add_u32_e32 v23, 0xa0, v144
	v_ldexp_f32 v22, v32, v22
	v_fmamk_f32 v22, v22, 0x30800000, v154
	v_mul_f32_e32 v32, 0x4b800000, v22
	v_cmp_gt_f32_e32 vcc, s56, v22
	s_nop 1
	v_cndmask_b32_e32 v22, v22, v32, vcc
	v_rsq_f32_e32 v32, v22
	v_mad_u32_u24 v22, v23, s57, v122
	s_nop 0
	s_nop 0
	v_mul_f32_e32 v33, 0x45800000, v32
	v_cndmask_b32_e32 v32, v32, v33, vcc
	v_pk_mul_f32 v[18:19], v[18:19], v[32:33] op_sel_hi:[1,0]
	v_pk_mul_f32 v[34:35], v[34:35], v[32:33] op_sel_hi:[1,0]
	v_pk_mul_f32 v[24:25], v[24:25], v[32:33] op_sel_hi:[1,0]
	v_pk_mul_f32 v[28:29], v[28:29], v[32:33] op_sel_hi:[1,0]
	v_pk_mul_f32 v[26:27], v[26:27], v[32:33] op_sel_hi:[1,0]
	v_pk_mul_f32 v[30:31], v[30:31], v[32:33] op_sel_hi:[1,0]
	v_pk_mul_f32 v[16:17], v[16:17], v[32:33] op_sel_hi:[1,0]
	v_pk_mul_f32 v[20:21], v[20:21], v[32:33] op_sel_hi:[1,0]
	v_mul_f32_e32 v41, 0xbfb8aa3b, v19
	v_mul_f32_e32 v32, 0xbfb8aa3b, v35
	v_mul_f32_e32 v33, 0xbfb8aa3b, v25
	v_mul_f32_e32 v36, 0xbfb8aa3b, v29
	v_mul_f32_e32 v37, 0xbfb8aa3b, v27
	v_mul_f32_e32 v38, 0xbfb8aa3b, v31
	v_mul_f32_e32 v39, 0xbfb8aa3b, v17
	v_mul_f32_e32 v40, 0xbfb8aa3b, v21
	v_exp_f32_e32 v41, v41
	v_exp_f32_e32 v32, v32
	v_exp_f32_e32 v33, v33
	v_exp_f32_e32 v36, v36
	v_exp_f32_e32 v37, v37
	v_exp_f32_e32 v38, v38
	v_exp_f32_e32 v39, v39
	v_exp_f32_e32 v40, v40
	v_add_f32_e32 v41, 1.0, v41
	v_add_f32_e32 v32, 1.0, v32
	v_add_f32_e32 v33, 1.0, v33
	v_add_f32_e32 v36, 1.0, v36
	v_add_f32_e32 v37, 1.0, v37
	v_add_f32_e32 v38, 1.0, v38
	v_add_f32_e32 v39, 1.0, v39
	v_add_f32_e32 v40, 1.0, v40
	v_rcp_f32_e32 v41, v41
	v_rcp_f32_e32 v32, v32
	v_rcp_f32_e32 v33, v33
	v_rcp_f32_e32 v36, v36
	v_rcp_f32_e32 v37, v37
	v_rcp_f32_e32 v38, v38
	v_rcp_f32_e32 v39, v39
	v_rcp_f32_e32 v40, v40
	v_mul_f32_e32 v19, v19, v41
	v_mul_f32_e32 v32, v35, v32
	v_mul_f32_e32 v25, v25, v33
	v_mul_f32_e32 v29, v29, v36
	v_mul_f32_e32 v27, v27, v37
	v_mul_f32_e32 v31, v31, v38
	v_mul_f32_e32 v17, v17, v39
	v_mul_f32_e32 v21, v21, v40
	v_mul_f32_e32 v19, v18, v19
	v_mul_f32_e32 v32, v34, v32
	v_mul_f32_e32 v24, v24, v25
	v_mul_f32_e32 v25, v28, v29
	v_mul_f32_e32 v26, v26, v27
	v_mul_f32_e32 v27, v30, v31
	v_mul_f32_e32 v28, v16, v17
	v_mul_f32_e32 v20, v20, v21
	v_cvt_pk_bf16_f32 v16, v32, v24
	v_cvt_pk_bf16_f32 v17, v25, v26
	v_cvt_pk_bf16_f32 v18, v27, v28
	v_cvt_pk_bf16_f32 v19, v20, v19
	global_store_dwordx4 v22, v[16:19], s[18:19]
	global_load_dwordx2 v[16:17], v[146:147], off offset:1408
	s_andn2_b64 vcc, exec, s[8:9]
	v_mov_b32_e32 v18, v12
	v_mov_b32_e32 v12, v14
	v_mov_b32_e32 v14, v8
	v_mov_b32_e32 v8, v10
	v_mov_b32_e32 v19, v4
	v_mov_b32_e32 v4, v13
	v_mov_b32_e32 v13, v6
	v_mov_b32_e32 v6, v15
	v_mov_b32_e32 v15, v0
	v_mov_b32_e32 v0, v9
	v_mov_b32_e32 v9, v2
	v_mov_b32_e32 v2, v11
	s_mov_b64 s[8:9], -1
	s_waitcnt vmcnt(0)
	v_ffbh_u32_e32 v10, v17
	v_min_u32_e32 v20, 32, v10
	v_lshlrev_b64 v[10:11], v20, v[16:17]
	v_min_u32_e32 v10, 1, v10
	v_or_b32_e32 v10, v11, v10
	v_cvt_f32_u32_e32 v10, v10
	v_sub_u32_e32 v16, 32, v20
	v_add_u32_e32 v11, 0xb0, v144
	v_ldexp_f32 v10, v10, v16
	v_fmamk_f32 v10, v10, 0x30800000, v154
	v_mul_f32_e32 v16, 0x4b800000, v10
	v_cmp_gt_f32_e64 s[10:11], s56, v10
	s_nop 1
	v_cndmask_b32_e64 v10, v10, v16, s[10:11]
	v_rsq_f32_e32 v16, v10
	v_mad_u32_u24 v10, v11, s57, v122
	s_nop 0
	s_nop 0
	v_mul_f32_e32 v17, 0x45800000, v16
	v_cndmask_b32_e64 v16, v16, v17, s[10:11]
	v_pk_mul_f32 v[2:3], v[2:3], v[16:17] op_sel_hi:[1,0]
	v_pk_mul_f32 v[18:19], v[18:19], v[16:17] op_sel_hi:[1,0]
	v_pk_mul_f32 v[4:5], v[4:5], v[16:17] op_sel_hi:[1,0]
	v_pk_mul_f32 v[12:13], v[12:13], v[16:17] op_sel_hi:[1,0]
	v_pk_mul_f32 v[6:7], v[6:7], v[16:17] op_sel_hi:[1,0]
	v_pk_mul_f32 v[14:15], v[14:15], v[16:17] op_sel_hi:[1,0]
	v_pk_mul_f32 v[0:1], v[0:1], v[16:17] op_sel_hi:[1,0]
	v_pk_mul_f32 v[8:9], v[8:9], v[16:17] op_sel_hi:[1,0]
	v_mul_f32_e32 v25, 0xbfb8aa3b, v3
	v_mul_f32_e32 v16, 0xbfb8aa3b, v19
	v_mul_f32_e32 v17, 0xbfb8aa3b, v5
	v_mul_f32_e32 v20, 0xbfb8aa3b, v13
	v_mul_f32_e32 v21, 0xbfb8aa3b, v7
	v_mul_f32_e32 v22, 0xbfb8aa3b, v15
	v_mul_f32_e32 v23, 0xbfb8aa3b, v1
	v_mul_f32_e32 v24, 0xbfb8aa3b, v9
	v_exp_f32_e32 v25, v25
	v_exp_f32_e32 v16, v16
	v_exp_f32_e32 v17, v17
	v_exp_f32_e32 v20, v20
	v_exp_f32_e32 v21, v21
	v_exp_f32_e32 v22, v22
	v_exp_f32_e32 v23, v23
	v_exp_f32_e32 v24, v24
	v_add_f32_e32 v25, 1.0, v25
	v_add_f32_e32 v16, 1.0, v16
	v_add_f32_e32 v17, 1.0, v17
	v_add_f32_e32 v20, 1.0, v20
	v_add_f32_e32 v21, 1.0, v21
	v_add_f32_e32 v22, 1.0, v22
	v_add_f32_e32 v23, 1.0, v23
	v_add_f32_e32 v24, 1.0, v24
	v_rcp_f32_e32 v25, v25
	v_rcp_f32_e32 v16, v16
	v_rcp_f32_e32 v17, v17
	v_rcp_f32_e32 v20, v20
	v_rcp_f32_e32 v21, v21
	v_rcp_f32_e32 v22, v22
	v_rcp_f32_e32 v23, v23
	v_rcp_f32_e32 v24, v24
	v_mul_f32_e32 v3, v3, v25
	v_mul_f32_e32 v16, v19, v16
	v_mul_f32_e32 v5, v5, v17
	v_mul_f32_e32 v13, v13, v20
	v_mul_f32_e32 v7, v7, v21
	v_mul_f32_e32 v15, v15, v22
	v_mul_f32_e32 v1, v1, v23
	v_mul_f32_e32 v9, v9, v24
	v_mul_f32_e32 v3, v2, v3
	v_mul_f32_e32 v16, v18, v16
	v_mul_f32_e32 v4, v4, v5
	v_mul_f32_e32 v5, v12, v13
	v_mul_f32_e32 v6, v6, v7
	v_mul_f32_e32 v7, v14, v15
	v_mul_f32_e32 v12, v0, v1
	v_mul_f32_e32 v8, v8, v9
	v_cvt_pk_bf16_f32 v0, v16, v4
	v_cvt_pk_bf16_f32 v1, v5, v6
	v_cvt_pk_bf16_f32 v2, v7, v12
	v_cvt_pk_bf16_f32 v3, v8, v3
	global_store_dwordx4 v10, v[0:3], s[18:19]
	s_cbranch_vccnz .LBB0_1825
	s_andn2_b64 vcc, exec, s[14:15]
	s_cbranch_vccnz .LBB0_1824
	s_barrier
	s_branch .LBB0_1824
